# fill_rstd: loads of all four blocks issued first, one wait, then the reductions (v51 + fr; original banded item mapping)
# speedup vs baseline: 1.0075x; 1.0075x over previous
.LBB0_345:
	s_cmp_eq_u32 s57, 3
	s_cselect_b64 s[0:1], -1, 0
	v_writelane_b32 v255, s0, 21
	s_nop 1
	v_writelane_b32 v255, s1, 22
	s_and_b64 s[0:1], s[0:1], exec
	s_cselect_b32 s5, 0, s57
	s_cmp_eq_u32 s57, 0
	s_cselect_b64 s[0:1], -1, 0
	v_writelane_b32 v255, s0, 23
	s_cmp_eq_u32 s57, 2
	s_nop 0
	v_writelane_b32 v255, s1, 24
	s_cselect_b64 s[0:1], -1, 0
	v_writelane_b32 v255, s0, 25
	s_nop 1
	v_writelane_b32 v255, s1, 26
	s_and_b64 s[0:1], s[0:1], exec
	s_mov_b32 s0, 0x380000
	s_cselect_b32 s4, s0, 0x500000
	s_cmp_eq_u32 s57, 1
	s_cselect_b64 s[0:1], -1, 0
	v_writelane_b32 v255, s0, 27
	s_nop 1
	v_writelane_b32 v255, s1, 28
	s_and_b64 s[0:1], s[0:1], exec
	s_cselect_b32 s56, 0x180000, s4
	s_cmp_lg_u32 s5, 0
	s_cselect_b64 s[10:11], -1, 0
	v_writelane_b32 v255, s5, 29
	s_and_b64 vcc, exec, s[10:11]
	s_mov_b64 s[0:1], -1
	s_cbranch_vccz .LBB0_740
	s_cmp_lt_i32 s57, 2
	s_cbranch_scc1 .LBB0_455
	s_cmp_eq_u32 s57, 2
	s_cbranch_scc0 .LBB0_454
	s_mov_b64 s[38:39], s[76:77]
	s_mov_b64 s[40:41], s[76:77]
	s_mov_b64 s[0:1], s[76:77]
	v_mov_b32_e32 v0, v252
	v_readlane_b32 s4, v255, 4
	v_ashrrev_i32_e32 v4, 8, v0
	s_waitcnt vmcnt(0)
	v_and_b32_e32 v3, 0xff, v0
	v_mov_b64_e32 v[0:1], s[2:3]
	v_lshl_add_u32 v2, v3, 2, s4
	v_mad_i64_i32 v[0:1], s[4:5], v4, s78, v[0:1]
	s_add_u32 s0, s0, 0x1ac00000
	s_mov_b64 s[4:5], 0x300
	s_addc_u32 s1, s1, 0
	v_cmp_gt_i64_e32 vcc, s[4:5], v[0:1]
	v_mov_b32_e32 v102, 0
	v_mov_b32_e32 v103, 0
	v_mov_b32_e32 v104, 0
	v_mov_b32_e32 v105, 0
	s_and_saveexec_b64 s[42:43], vcc
	s_cbranch_execz .LBB0_350
	v_ashrrev_i32_e32 v1, 31, v0
	v_lshrrev_b32_e32 v1, 29, v1
	v_add_u32_e32 v1, v0, v1
	v_ashrrev_i32_e32 v5, 3, v1
	v_and_b32_e32 v1, -8, v1
	v_sub_u32_e32 v0, v0, v1
	v_cmp_gt_i32_e32 vcc, 0, v0
	s_mov_b32 s4, 0x2aaaaaab
	s_nop 0
	v_cndmask_b32_e32 v1, v246, v240, vcc
	v_mul_lo_u32 v0, v0, v1
	v_add_u32_e32 v0, v0, v5
	v_mul_hi_i32 v1, v0, s4
	v_lshrrev_b32_e32 v5, 31, v1
	v_ashrrev_i32_e32 v1, 3, v1
	v_add_u32_e32 v1, v1, v5
	v_lshlrev_b32_e32 v5, 3, v1
	v_sub_u32_e32 v6, 0x80, v5
	v_min_i32_e32 v6, 8, v6
	v_sub_u32_e32 v7, 0, v6
	v_max_i32_e32 v6, v6, v7
	v_cvt_f32_u32_e32 v7, v6
	v_mul_lo_u32 v1, v1, 48
	v_sub_u32_e32 v0, v0, v1
	v_sub_u32_e32 v8, 0, v0
	v_rcp_iflag_f32_e32 v7, v7
	v_ashrrev_i32_e32 v1, 31, v0
	v_max_i32_e32 v0, v0, v8
	v_sub_u32_e32 v8, 0, v6
	v_mul_f32_e32 v7, 0x4f7ffffe, v7
	v_cvt_u32_f32_e32 v7, v7
	v_mul_lo_u32 v8, v8, v7
	v_mul_hi_u32 v8, v7, v8
	v_add_u32_e32 v7, v7, v8
	v_mul_hi_u32 v7, v0, v7
	v_mul_lo_u32 v7, v7, v6
	v_sub_u32_e32 v0, v0, v7
	v_sub_u32_e32 v7, v0, v6
	v_cmp_ge_u32_e32 vcc, v0, v6
	s_nop 1
	v_cndmask_b32_e32 v0, v0, v7, vcc
	v_sub_u32_e32 v7, v0, v6
	v_cmp_ge_u32_e32 vcc, v0, v6
	s_nop 1
	v_cndmask_b32_e32 v0, v0, v7, vcc
	v_xor_b32_e32 v0, v0, v1
	v_sub_u32_e32 v0, v0, v1
	v_add_u32_e32 v0, v5, v0
	v_lshl_or_b32 v0, v0, 8, v3
	v_ashrrev_i32_e32 v1, 31, v0
	v_lshlrev_b64 v[0:1], 6, v[0:1]
	v_lshl_add_u64 v[0:1], s[0:1], 0, v[0:1]
	global_load_dwordx4 v[34:37], v[0:1], off
	global_load_dwordx4 v[38:41], v[0:1], off offset:32
	global_load_dwordx4 v[42:45], v[0:1], off offset:16
	global_load_dwordx4 v[46:49], v[0:1], off offset:48
	v_lshl_add_u32 v98, v4, 10, v2
	v_mov_b32_e32 v102, 1
.LBB0_350:
	s_or_b64 exec, exec, s[42:43]
	v_add_u32_e32 v5, 2, v4
	v_mov_b64_e32 v[0:1], s[2:3]
	v_mad_i64_i32 v[0:1], s[4:5], v5, s78, v[0:1]
	s_mov_b64 s[4:5], 0x300
	s_nop 0
	v_cmp_gt_i64_e32 vcc, s[4:5], v[0:1]
	s_and_saveexec_b64 s[42:43], vcc
	s_cbranch_execz .LBB0_352
	v_ashrrev_i32_e32 v1, 31, v0
	v_lshrrev_b32_e32 v1, 29, v1
	v_add_u32_e32 v1, v0, v1
	v_ashrrev_i32_e32 v6, 3, v1
	v_and_b32_e32 v1, -8, v1
	v_sub_u32_e32 v0, v0, v1
	v_cmp_gt_i32_e32 vcc, 0, v0
	s_mov_b32 s4, 0x2aaaaaab
	s_nop 0
	v_cndmask_b32_e32 v1, v246, v240, vcc
	v_mul_lo_u32 v0, v0, v1
	v_add_u32_e32 v0, v0, v6
	v_mul_hi_i32 v1, v0, s4
	v_lshrrev_b32_e32 v6, 31, v1
	v_ashrrev_i32_e32 v1, 3, v1
	v_add_u32_e32 v1, v1, v6
	v_lshlrev_b32_e32 v6, 3, v1
	v_sub_u32_e32 v7, 0x80, v6
	v_min_i32_e32 v7, 8, v7
	v_sub_u32_e32 v8, 0, v7
	v_max_i32_e32 v7, v7, v8
	v_cvt_f32_u32_e32 v8, v7
	v_mul_lo_u32 v1, v1, 48
	v_sub_u32_e32 v0, v0, v1
	v_sub_u32_e32 v9, 0, v0
	v_rcp_iflag_f32_e32 v8, v8
	v_ashrrev_i32_e32 v1, 31, v0
	v_max_i32_e32 v0, v0, v9
	v_sub_u32_e32 v9, 0, v7
	v_mul_f32_e32 v8, 0x4f7ffffe, v8
	v_cvt_u32_f32_e32 v8, v8
	v_mul_lo_u32 v9, v9, v8
	v_mul_hi_u32 v9, v8, v9
	v_add_u32_e32 v8, v8, v9
	v_mul_hi_u32 v8, v0, v8
	v_mul_lo_u32 v8, v8, v7
	v_sub_u32_e32 v0, v0, v8
	v_sub_u32_e32 v8, v0, v7
	v_cmp_ge_u32_e32 vcc, v0, v7
	s_nop 1
	v_cndmask_b32_e32 v0, v0, v8, vcc
	v_sub_u32_e32 v8, v0, v7
	v_cmp_ge_u32_e32 vcc, v0, v7
	s_nop 1
	v_cndmask_b32_e32 v0, v0, v8, vcc
	v_xor_b32_e32 v0, v0, v1
	v_sub_u32_e32 v0, v0, v1
	v_add_u32_e32 v0, v6, v0
	v_lshl_or_b32 v0, v0, 8, v3
	v_ashrrev_i32_e32 v1, 31, v0
	v_lshlrev_b64 v[0:1], 6, v[0:1]
	v_lshl_add_u64 v[0:1], s[0:1], 0, v[0:1]
	global_load_dwordx4 v[50:53], v[0:1], off
	global_load_dwordx4 v[54:57], v[0:1], off offset:32
	global_load_dwordx4 v[58:61], v[0:1], off offset:16
	global_load_dwordx4 v[62:65], v[0:1], off offset:48
	v_lshl_add_u32 v99, v5, 10, v2
	v_mov_b32_e32 v103, 1
.LBB0_352:
	s_or_b64 exec, exec, s[42:43]
	v_add_u32_e32 v5, 4, v4
	v_mov_b64_e32 v[0:1], s[2:3]
	v_mad_i64_i32 v[0:1], s[4:5], v5, s78, v[0:1]
	s_mov_b64 s[4:5], 0x300
	s_nop 0
	v_cmp_gt_i64_e32 vcc, s[4:5], v[0:1]
	s_and_saveexec_b64 s[42:43], vcc
	s_cbranch_execz .LBB0_354
	v_ashrrev_i32_e32 v1, 31, v0
	v_lshrrev_b32_e32 v1, 29, v1
	v_add_u32_e32 v1, v0, v1
	v_ashrrev_i32_e32 v6, 3, v1
	v_and_b32_e32 v1, -8, v1
	v_sub_u32_e32 v0, v0, v1
	v_cmp_gt_i32_e32 vcc, 0, v0
	s_mov_b32 s4, 0x2aaaaaab
	s_nop 0
	v_cndmask_b32_e32 v1, v246, v240, vcc
	v_mul_lo_u32 v0, v0, v1
	v_add_u32_e32 v0, v0, v6
	v_mul_hi_i32 v1, v0, s4
	v_lshrrev_b32_e32 v6, 31, v1
	v_ashrrev_i32_e32 v1, 3, v1
	v_add_u32_e32 v1, v1, v6
	v_lshlrev_b32_e32 v6, 3, v1
	v_sub_u32_e32 v7, 0x80, v6
	v_min_i32_e32 v7, 8, v7
	v_sub_u32_e32 v8, 0, v7
	v_max_i32_e32 v7, v7, v8
	v_cvt_f32_u32_e32 v8, v7
	v_mul_lo_u32 v1, v1, 48
	v_sub_u32_e32 v0, v0, v1
	v_sub_u32_e32 v9, 0, v0
	v_rcp_iflag_f32_e32 v8, v8
	v_ashrrev_i32_e32 v1, 31, v0
	v_max_i32_e32 v0, v0, v9
	v_sub_u32_e32 v9, 0, v7
	v_mul_f32_e32 v8, 0x4f7ffffe, v8
	v_cvt_u32_f32_e32 v8, v8
	v_mul_lo_u32 v9, v9, v8
	v_mul_hi_u32 v9, v8, v9
	v_add_u32_e32 v8, v8, v9
	v_mul_hi_u32 v8, v0, v8
	v_mul_lo_u32 v8, v8, v7
	v_sub_u32_e32 v0, v0, v8
	v_sub_u32_e32 v8, v0, v7
	v_cmp_ge_u32_e32 vcc, v0, v7
	s_nop 1
	v_cndmask_b32_e32 v0, v0, v8, vcc
	v_sub_u32_e32 v8, v0, v7
	v_cmp_ge_u32_e32 vcc, v0, v7
	s_nop 1
	v_cndmask_b32_e32 v0, v0, v8, vcc
	v_xor_b32_e32 v0, v0, v1
	v_sub_u32_e32 v0, v0, v1
	v_add_u32_e32 v0, v6, v0
	v_lshl_or_b32 v0, v0, 8, v3
	v_ashrrev_i32_e32 v1, 31, v0
	v_lshlrev_b64 v[0:1], 6, v[0:1]
	v_lshl_add_u64 v[0:1], s[0:1], 0, v[0:1]
	global_load_dwordx4 v[66:69], v[0:1], off
	global_load_dwordx4 v[70:73], v[0:1], off offset:32
	global_load_dwordx4 v[74:77], v[0:1], off offset:16
	global_load_dwordx4 v[78:81], v[0:1], off offset:48
	v_lshl_add_u32 v100, v5, 10, v2
	v_mov_b32_e32 v104, 1
.LBB0_354:
	s_or_b64 exec, exec, s[42:43]
	v_add_u32_e32 v4, 6, v4
	v_mov_b64_e32 v[0:1], s[2:3]
	v_mad_i64_i32 v[0:1], s[4:5], v4, s78, v[0:1]
	s_mov_b64 s[4:5], 0x300
	s_nop 0
	v_cmp_gt_i64_e32 vcc, s[4:5], v[0:1]
	s_and_saveexec_b64 s[42:43], vcc
	s_cbranch_execz .LBB0_356
	v_ashrrev_i32_e32 v1, 31, v0
	v_lshrrev_b32_e32 v1, 29, v1
	v_add_u32_e32 v1, v0, v1
	v_ashrrev_i32_e32 v5, 3, v1
	v_and_b32_e32 v1, -8, v1
	v_sub_u32_e32 v0, v0, v1
	v_cmp_gt_i32_e32 vcc, 0, v0
	s_mov_b32 s4, 0x2aaaaaab
	s_nop 0
	v_cndmask_b32_e32 v1, v246, v240, vcc
	v_mul_lo_u32 v0, v0, v1
	v_add_u32_e32 v0, v0, v5
	v_mul_hi_i32 v1, v0, s4
	v_lshrrev_b32_e32 v5, 31, v1
	v_ashrrev_i32_e32 v1, 3, v1
	v_add_u32_e32 v1, v1, v5
	v_lshlrev_b32_e32 v5, 3, v1
	v_sub_u32_e32 v6, 0x80, v5
	v_min_i32_e32 v6, 8, v6
	v_sub_u32_e32 v7, 0, v6
	v_max_i32_e32 v6, v6, v7
	v_cvt_f32_u32_e32 v7, v6
	v_mul_lo_u32 v1, v1, 48
	v_sub_u32_e32 v0, v0, v1
	v_sub_u32_e32 v8, 0, v0
	v_rcp_iflag_f32_e32 v7, v7
	v_ashrrev_i32_e32 v1, 31, v0
	v_max_i32_e32 v0, v0, v8
	v_sub_u32_e32 v8, 0, v6
	v_mul_f32_e32 v7, 0x4f7ffffe, v7
	v_cvt_u32_f32_e32 v7, v7
	v_mul_lo_u32 v8, v8, v7
	v_mul_hi_u32 v8, v7, v8
	v_add_u32_e32 v7, v7, v8
	v_mul_hi_u32 v7, v0, v7
	v_mul_lo_u32 v7, v7, v6
	v_sub_u32_e32 v0, v0, v7
	v_sub_u32_e32 v7, v0, v6
	v_cmp_ge_u32_e32 vcc, v0, v6
	s_nop 1
	v_cndmask_b32_e32 v0, v0, v7, vcc
	v_sub_u32_e32 v7, v0, v6
	v_cmp_ge_u32_e32 vcc, v0, v6
	s_nop 1
	v_cndmask_b32_e32 v0, v0, v7, vcc
	v_xor_b32_e32 v0, v0, v1
	v_sub_u32_e32 v0, v0, v1
	v_add_u32_e32 v0, v5, v0
	v_lshl_or_b32 v0, v0, 8, v3
	v_ashrrev_i32_e32 v1, 31, v0
	v_lshlrev_b64 v[0:1], 6, v[0:1]
	v_lshl_add_u64 v[0:1], s[0:1], 0, v[0:1]
	global_load_dwordx4 v[82:85], v[0:1], off
	global_load_dwordx4 v[86:89], v[0:1], off offset:32
	global_load_dwordx4 v[90:93], v[0:1], off offset:16
	global_load_dwordx4 v[94:97], v[0:1], off offset:48
	v_lshl_add_u32 v101, v4, 10, v2
	v_mov_b32_e32 v105, 1
.LBB0_356:
	s_or_b64 exec, exec, s[42:43]
	s_waitcnt vmcnt(0)
	v_cmp_ne_u32_e32 vcc, 0, v102
	s_and_saveexec_b64 s[42:43], vcc
	s_cbranch_execz .Lfr_0_0
	v_mov_b32_e32 v0, v34
	v_mov_b32_e32 v1, v38
	v_mov_b32_e32 v38, v35
	v_mov_b32_e32 v34, v36
	v_mov_b32_e32 v35, v40
	v_mov_b32_e32 v40, v37
	v_mov_b32_e32 v36, v42
	v_mov_b32_e32 v37, v46
	v_mov_b32_e32 v46, v43
	v_mov_b32_e32 v42, v44
	v_mov_b32_e32 v43, v48
	v_mov_b32_e32 v48, v45
	v_pk_add_f32 v[0:1], v[0:1], v[38:39]
	v_pk_add_f32 v[34:35], v[34:35], v[40:41]
	v_pk_add_f32 v[36:37], v[36:37], v[46:47]
	v_pk_add_f32 v[38:39], v[42:43], v[48:49]
	v_pk_add_f32 v[0:1], v[0:1], v[34:35]
	v_pk_add_f32 v[34:35], v[36:37], v[38:39]
	s_nop 0
	v_pk_add_f32 v[0:1], v[0:1], v[34:35]
	s_nop 0
	v_add_f32_e32 v0, v0, v1
	v_fmamk_f32 v0, v0, 0x3a800000, v236
	v_rsq_f32_e32 v0, v0
	ds_write_b32 v98, v0
.Lfr_0_0:
	s_or_b64 exec, exec, s[42:43]
	v_cmp_ne_u32_e32 vcc, 0, v103
	s_and_saveexec_b64 s[42:43], vcc
	s_cbranch_execz .Lfr_0_1
	v_mov_b32_e32 v0, v50
	v_mov_b32_e32 v1, v54
	v_mov_b32_e32 v54, v51
	v_mov_b32_e32 v50, v52
	v_mov_b32_e32 v51, v56
	v_mov_b32_e32 v56, v53
	v_mov_b32_e32 v52, v58
	v_mov_b32_e32 v53, v62
	v_mov_b32_e32 v62, v59
	v_mov_b32_e32 v58, v60
	v_mov_b32_e32 v59, v64
	v_mov_b32_e32 v64, v61
	v_pk_add_f32 v[0:1], v[0:1], v[54:55]
	v_pk_add_f32 v[50:51], v[50:51], v[56:57]
	v_pk_add_f32 v[52:53], v[52:53], v[62:63]
	v_pk_add_f32 v[54:55], v[58:59], v[64:65]
	v_pk_add_f32 v[0:1], v[0:1], v[50:51]
	v_pk_add_f32 v[50:51], v[52:53], v[54:55]
	s_nop 0
	v_pk_add_f32 v[0:1], v[0:1], v[50:51]
	s_nop 0
	v_add_f32_e32 v0, v0, v1
	v_fmamk_f32 v0, v0, 0x3a800000, v236
	v_rsq_f32_e32 v0, v0
	ds_write_b32 v99, v0
.Lfr_0_1:
	s_or_b64 exec, exec, s[42:43]
	v_cmp_ne_u32_e32 vcc, 0, v104
	s_and_saveexec_b64 s[42:43], vcc
	s_cbranch_execz .Lfr_0_2
	v_mov_b32_e32 v0, v66
	v_mov_b32_e32 v1, v70
	v_mov_b32_e32 v70, v67
	v_mov_b32_e32 v66, v68
	v_mov_b32_e32 v67, v72
	v_mov_b32_e32 v72, v69
	v_mov_b32_e32 v68, v74
	v_mov_b32_e32 v69, v78
	v_mov_b32_e32 v78, v75
	v_mov_b32_e32 v74, v76
	v_mov_b32_e32 v75, v80
	v_mov_b32_e32 v80, v77
	v_pk_add_f32 v[0:1], v[0:1], v[70:71]
	v_pk_add_f32 v[66:67], v[66:67], v[72:73]
	v_pk_add_f32 v[68:69], v[68:69], v[78:79]
	v_pk_add_f32 v[70:71], v[74:75], v[80:81]
	v_pk_add_f32 v[0:1], v[0:1], v[66:67]
	v_pk_add_f32 v[66:67], v[68:69], v[70:71]
	s_nop 0
	v_pk_add_f32 v[0:1], v[0:1], v[66:67]
	s_nop 0
	v_add_f32_e32 v0, v0, v1
	v_fmamk_f32 v0, v0, 0x3a800000, v236
	v_rsq_f32_e32 v0, v0
	ds_write_b32 v100, v0
.Lfr_0_2:
	s_or_b64 exec, exec, s[42:43]
	v_cmp_ne_u32_e32 vcc, 0, v105
	s_and_saveexec_b64 s[42:43], vcc
	s_cbranch_execz .Lfr_0_3
	v_mov_b32_e32 v0, v82
	v_mov_b32_e32 v1, v86
	v_mov_b32_e32 v86, v83
	v_mov_b32_e32 v82, v84
	v_mov_b32_e32 v83, v88
	v_mov_b32_e32 v88, v85
	v_mov_b32_e32 v84, v90
	v_mov_b32_e32 v85, v94
	v_mov_b32_e32 v94, v91
	v_mov_b32_e32 v90, v92
	v_mov_b32_e32 v91, v96
	v_mov_b32_e32 v96, v93
	v_pk_add_f32 v[0:1], v[0:1], v[86:87]
	v_pk_add_f32 v[82:83], v[82:83], v[88:89]
	v_pk_add_f32 v[84:85], v[84:85], v[94:95]
	v_pk_add_f32 v[86:87], v[90:91], v[96:97]
	v_pk_add_f32 v[0:1], v[0:1], v[82:83]
	v_pk_add_f32 v[82:83], v[84:85], v[86:87]
	s_nop 0
	v_pk_add_f32 v[0:1], v[0:1], v[82:83]
	s_nop 0
	v_add_f32_e32 v0, v0, v1
	v_fmamk_f32 v0, v0, 0x3a800000, v236
	v_rsq_f32_e32 v0, v0
	ds_write_b32 v101, v0

.LBB0_455:
	s_andn2_b64 vcc, exec, s[0:1]
	s_cbranch_vccnz .LBB0_739
	s_cmp_lg_u32 s57, 1
	s_cbranch_scc1 .LBB0_739
	s_mov_b64 s[38:39], s[76:77]
	s_mov_b64 s[0:1], s[76:77]
	s_mov_b64 s[4:5], s[76:77]
	v_mov_b32_e32 v0, v252
	s_add_u32 s40, s4, 0x1a800000
	v_ashrrev_i32_e32 v4, 8, v0
	s_waitcnt vmcnt(0)
	v_and_b32_e32 v3, 0xff, v0
	v_readlane_b32 s4, v255, 4
	v_mov_b64_e32 v[0:1], s[2:3]
	s_addc_u32 s41, s5, 0
	v_lshl_add_u32 v2, v3, 2, s4
	v_mad_i64_i32 v[0:1], s[4:5], v4, s78, v[0:1]
	s_mov_b64 s[4:5], 0x400
	s_nop 0
	v_cmp_gt_i64_e32 vcc, s[4:5], v[0:1]
	v_mov_b32_e32 v102, 0
	v_mov_b32_e32 v103, 0
	v_mov_b32_e32 v104, 0
	v_mov_b32_e32 v105, 0
	s_and_saveexec_b64 s[42:43], vcc
	s_cbranch_execz .LBB0_463
	v_ashrrev_i32_e32 v1, 31, v0
	v_lshrrev_b32_e32 v1, 29, v1
	v_add_u32_e32 v1, v0, v1
	v_and_b32_e32 v5, -8, v1
	v_sub_u32_e32 v5, v0, v5
	v_cmp_lt_i32_e32 vcc, -1, v5
	s_and_saveexec_b64 s[4:5], vcc
	s_xor_b64 s[44:45], exec, s[4:5]
	v_lshlrev_b32_e32 v0, 7, v5
	s_andn2_saveexec_b64 s[44:45], s[44:45]
	v_lshl_add_u32 v0, v5, 7, v5
	s_or_b64 exec, exec, s[44:45]
	v_ashrrev_i32_e32 v1, 3, v1
	v_add_u32_e32 v0, v0, v1
	v_ashrrev_i32_e32 v1, 31, v0
	v_lshrrev_b32_e32 v1, 26, v1
	v_add_u32_e32 v1, v0, v1
	v_ashrrev_i32_e32 v5, 6, v1
	v_lshlrev_b32_e32 v5, 3, v5
	v_sub_u32_e32 v6, 0x80, v5
	v_min_i32_e32 v6, 8, v6
	v_sub_u32_e32 v7, 0, v6
	v_max_i32_e32 v6, v6, v7
	v_cvt_f32_u32_e32 v7, v6
	v_and_b32_e32 v1, 0xffffffc0, v1
	v_sub_u32_e32 v0, v0, v1
	v_sub_u32_e32 v8, 0, v0
	v_rcp_iflag_f32_e32 v7, v7
	v_ashrrev_i32_e32 v1, 31, v0
	v_max_i32_e32 v0, v0, v8
	v_sub_u32_e32 v8, 0, v6
	v_mul_f32_e32 v7, 0x4f7ffffe, v7
	v_cvt_u32_f32_e32 v7, v7
	v_mul_lo_u32 v8, v8, v7
	v_mul_hi_u32 v8, v7, v8
	v_add_u32_e32 v7, v7, v8
	v_mul_hi_u32 v7, v0, v7
	v_mul_lo_u32 v7, v7, v6
	v_sub_u32_e32 v0, v0, v7
	v_sub_u32_e32 v7, v0, v6
	v_cmp_ge_u32_e32 vcc, v0, v6
	s_nop 1
	v_cndmask_b32_e32 v0, v0, v7, vcc
	v_sub_u32_e32 v7, v0, v6
	v_cmp_ge_u32_e32 vcc, v0, v6
	s_nop 1
	v_cndmask_b32_e32 v0, v0, v7, vcc
	v_xor_b32_e32 v0, v0, v1
	v_sub_u32_e32 v0, v0, v1
	v_add_u32_e32 v0, v5, v0
	v_lshl_or_b32 v0, v0, 8, v3
	v_ashrrev_i32_e32 v1, 31, v0
	v_lshlrev_b64 v[0:1], 6, v[0:1]
	v_lshl_add_u64 v[0:1], s[40:41], 0, v[0:1]
	global_load_dwordx4 v[34:37], v[0:1], off
	global_load_dwordx4 v[38:41], v[0:1], off offset:32
	global_load_dwordx4 v[42:45], v[0:1], off offset:16
	global_load_dwordx4 v[46:49], v[0:1], off offset:48
	v_lshl_add_u32 v98, v4, 10, v2
	v_mov_b32_e32 v102, 1
.LBB0_463:
	s_or_b64 exec, exec, s[42:43]
	v_add_u32_e32 v5, 2, v4
	v_mov_b64_e32 v[0:1], s[2:3]
	v_mad_i64_i32 v[0:1], s[4:5], v5, s78, v[0:1]
	s_mov_b64 s[4:5], 0x400
	s_nop 0
	v_cmp_gt_i64_e32 vcc, s[4:5], v[0:1]
	s_and_saveexec_b64 s[42:43], vcc
	s_cbranch_execz .LBB0_469
	v_ashrrev_i32_e32 v1, 31, v0
	v_lshrrev_b32_e32 v1, 29, v1
	v_add_u32_e32 v1, v0, v1
	v_and_b32_e32 v6, -8, v1
	v_sub_u32_e32 v6, v0, v6
	v_cmp_lt_i32_e32 vcc, -1, v6
	s_and_saveexec_b64 s[4:5], vcc
	s_xor_b64 s[44:45], exec, s[4:5]
	v_lshlrev_b32_e32 v0, 7, v6
	s_andn2_saveexec_b64 s[44:45], s[44:45]
	v_lshl_add_u32 v0, v6, 7, v6
	s_or_b64 exec, exec, s[44:45]
	v_ashrrev_i32_e32 v1, 3, v1
	v_add_u32_e32 v0, v0, v1
	v_ashrrev_i32_e32 v1, 31, v0
	v_lshrrev_b32_e32 v1, 26, v1
	v_add_u32_e32 v1, v0, v1
	v_ashrrev_i32_e32 v6, 6, v1
	v_lshlrev_b32_e32 v6, 3, v6
	v_sub_u32_e32 v7, 0x80, v6
	v_min_i32_e32 v7, 8, v7
	v_sub_u32_e32 v8, 0, v7
	v_max_i32_e32 v7, v7, v8
	v_cvt_f32_u32_e32 v8, v7
	v_and_b32_e32 v1, 0xffffffc0, v1
	v_sub_u32_e32 v0, v0, v1
	v_sub_u32_e32 v9, 0, v0
	v_rcp_iflag_f32_e32 v8, v8
	v_ashrrev_i32_e32 v1, 31, v0
	v_max_i32_e32 v0, v0, v9
	v_sub_u32_e32 v9, 0, v7
	v_mul_f32_e32 v8, 0x4f7ffffe, v8
	v_cvt_u32_f32_e32 v8, v8
	v_mul_lo_u32 v9, v9, v8
	v_mul_hi_u32 v9, v8, v9
	v_add_u32_e32 v8, v8, v9
	v_mul_hi_u32 v8, v0, v8
	v_mul_lo_u32 v8, v8, v7
	v_sub_u32_e32 v0, v0, v8
	v_sub_u32_e32 v8, v0, v7
	v_cmp_ge_u32_e32 vcc, v0, v7
	s_nop 1
	v_cndmask_b32_e32 v0, v0, v8, vcc
	v_sub_u32_e32 v8, v0, v7
	v_cmp_ge_u32_e32 vcc, v0, v7
	s_nop 1
	v_cndmask_b32_e32 v0, v0, v8, vcc
	v_xor_b32_e32 v0, v0, v1
	v_sub_u32_e32 v0, v0, v1
	v_add_u32_e32 v0, v6, v0
	v_lshl_or_b32 v0, v0, 8, v3
	v_ashrrev_i32_e32 v1, 31, v0
	v_lshlrev_b64 v[0:1], 6, v[0:1]
	v_lshl_add_u64 v[0:1], s[40:41], 0, v[0:1]
	global_load_dwordx4 v[50:53], v[0:1], off
	global_load_dwordx4 v[54:57], v[0:1], off offset:32
	global_load_dwordx4 v[58:61], v[0:1], off offset:16
	global_load_dwordx4 v[62:65], v[0:1], off offset:48
	v_lshl_add_u32 v99, v5, 10, v2
	v_mov_b32_e32 v103, 1
.LBB0_469:
	s_or_b64 exec, exec, s[42:43]
	v_add_u32_e32 v5, 4, v4
	v_mov_b64_e32 v[0:1], s[2:3]
	v_mad_i64_i32 v[0:1], s[4:5], v5, s78, v[0:1]
	s_mov_b64 s[4:5], 0x400
	s_nop 0
	v_cmp_gt_i64_e32 vcc, s[4:5], v[0:1]
	s_and_saveexec_b64 s[42:43], vcc
	s_cbranch_execz .LBB0_475
	v_ashrrev_i32_e32 v1, 31, v0
	v_lshrrev_b32_e32 v1, 29, v1
	v_add_u32_e32 v1, v0, v1
	v_and_b32_e32 v6, -8, v1
	v_sub_u32_e32 v6, v0, v6
	v_cmp_lt_i32_e32 vcc, -1, v6
	s_and_saveexec_b64 s[4:5], vcc
	s_xor_b64 s[44:45], exec, s[4:5]
	v_lshlrev_b32_e32 v0, 7, v6
	s_andn2_saveexec_b64 s[44:45], s[44:45]
	v_lshl_add_u32 v0, v6, 7, v6
	s_or_b64 exec, exec, s[44:45]
	v_ashrrev_i32_e32 v1, 3, v1
	v_add_u32_e32 v0, v0, v1
	v_ashrrev_i32_e32 v1, 31, v0
	v_lshrrev_b32_e32 v1, 26, v1
	v_add_u32_e32 v1, v0, v1
	v_ashrrev_i32_e32 v6, 6, v1
	v_lshlrev_b32_e32 v6, 3, v6
	v_sub_u32_e32 v7, 0x80, v6
	v_min_i32_e32 v7, 8, v7
	v_sub_u32_e32 v8, 0, v7
	v_max_i32_e32 v7, v7, v8
	v_cvt_f32_u32_e32 v8, v7
	v_and_b32_e32 v1, 0xffffffc0, v1
	v_sub_u32_e32 v0, v0, v1
	v_sub_u32_e32 v9, 0, v0
	v_rcp_iflag_f32_e32 v8, v8
	v_ashrrev_i32_e32 v1, 31, v0
	v_max_i32_e32 v0, v0, v9
	v_sub_u32_e32 v9, 0, v7
	v_mul_f32_e32 v8, 0x4f7ffffe, v8
	v_cvt_u32_f32_e32 v8, v8
	v_mul_lo_u32 v9, v9, v8
	v_mul_hi_u32 v9, v8, v9
	v_add_u32_e32 v8, v8, v9
	v_mul_hi_u32 v8, v0, v8
	v_mul_lo_u32 v8, v8, v7
	v_sub_u32_e32 v0, v0, v8
	v_sub_u32_e32 v8, v0, v7
	v_cmp_ge_u32_e32 vcc, v0, v7
	s_nop 1
	v_cndmask_b32_e32 v0, v0, v8, vcc
	v_sub_u32_e32 v8, v0, v7
	v_cmp_ge_u32_e32 vcc, v0, v7
	s_nop 1
	v_cndmask_b32_e32 v0, v0, v8, vcc
	v_xor_b32_e32 v0, v0, v1
	v_sub_u32_e32 v0, v0, v1
	v_add_u32_e32 v0, v6, v0
	v_lshl_or_b32 v0, v0, 8, v3
	v_ashrrev_i32_e32 v1, 31, v0
	v_lshlrev_b64 v[0:1], 6, v[0:1]
	v_lshl_add_u64 v[0:1], s[40:41], 0, v[0:1]
	global_load_dwordx4 v[66:69], v[0:1], off
	global_load_dwordx4 v[70:73], v[0:1], off offset:32
	global_load_dwordx4 v[74:77], v[0:1], off offset:16
	global_load_dwordx4 v[78:81], v[0:1], off offset:48
	v_lshl_add_u32 v100, v5, 10, v2
	v_mov_b32_e32 v104, 1
.LBB0_475:
	s_or_b64 exec, exec, s[42:43]
	v_add_u32_e32 v4, 6, v4
	v_mov_b64_e32 v[0:1], s[2:3]
	v_mad_i64_i32 v[0:1], s[4:5], v4, s78, v[0:1]
	s_mov_b64 s[4:5], 0x400
	s_nop 0
	v_cmp_gt_i64_e32 vcc, s[4:5], v[0:1]
	s_and_saveexec_b64 s[42:43], vcc
	s_cbranch_execz .LBB0_481
	v_ashrrev_i32_e32 v1, 31, v0
	v_lshrrev_b32_e32 v1, 29, v1
	v_add_u32_e32 v1, v0, v1
	v_and_b32_e32 v5, -8, v1
	v_sub_u32_e32 v5, v0, v5
	v_cmp_lt_i32_e32 vcc, -1, v5
	s_and_saveexec_b64 s[4:5], vcc
	s_xor_b64 s[44:45], exec, s[4:5]
	v_lshlrev_b32_e32 v0, 7, v5
	s_andn2_saveexec_b64 s[44:45], s[44:45]
	v_lshl_add_u32 v0, v5, 7, v5
	s_or_b64 exec, exec, s[44:45]
	v_ashrrev_i32_e32 v1, 3, v1
	v_add_u32_e32 v0, v0, v1
	v_ashrrev_i32_e32 v1, 31, v0
	v_lshrrev_b32_e32 v1, 26, v1
	v_add_u32_e32 v1, v0, v1
	v_ashrrev_i32_e32 v5, 6, v1
	v_lshlrev_b32_e32 v5, 3, v5
	v_sub_u32_e32 v6, 0x80, v5
	v_min_i32_e32 v6, 8, v6
	v_sub_u32_e32 v7, 0, v6
	v_max_i32_e32 v6, v6, v7
	v_cvt_f32_u32_e32 v7, v6
	v_and_b32_e32 v1, 0xffffffc0, v1
	v_sub_u32_e32 v0, v0, v1
	v_sub_u32_e32 v8, 0, v0
	v_rcp_iflag_f32_e32 v7, v7
	v_ashrrev_i32_e32 v1, 31, v0
	v_max_i32_e32 v0, v0, v8
	v_sub_u32_e32 v8, 0, v6
	v_mul_f32_e32 v7, 0x4f7ffffe, v7
	v_cvt_u32_f32_e32 v7, v7
	v_mul_lo_u32 v8, v8, v7
	v_mul_hi_u32 v8, v7, v8
	v_add_u32_e32 v7, v7, v8
	v_mul_hi_u32 v7, v0, v7
	v_mul_lo_u32 v7, v7, v6
	v_sub_u32_e32 v0, v0, v7
	v_sub_u32_e32 v7, v0, v6
	v_cmp_ge_u32_e32 vcc, v0, v6
	s_nop 1
	v_cndmask_b32_e32 v0, v0, v7, vcc
	v_sub_u32_e32 v7, v0, v6
	v_cmp_ge_u32_e32 vcc, v0, v6
	s_nop 1
	v_cndmask_b32_e32 v0, v0, v7, vcc
	v_xor_b32_e32 v0, v0, v1
	v_sub_u32_e32 v0, v0, v1
	v_add_u32_e32 v0, v5, v0
	v_lshl_or_b32 v0, v0, 8, v3
	v_ashrrev_i32_e32 v1, 31, v0
	v_lshlrev_b64 v[0:1], 6, v[0:1]
	v_lshl_add_u64 v[0:1], s[40:41], 0, v[0:1]
	global_load_dwordx4 v[82:85], v[0:1], off
	global_load_dwordx4 v[86:89], v[0:1], off offset:32
	global_load_dwordx4 v[90:93], v[0:1], off offset:16
	global_load_dwordx4 v[94:97], v[0:1], off offset:48
	v_lshl_add_u32 v101, v4, 10, v2
	v_mov_b32_e32 v105, 1

.LBB0_740:
	s_and_b64 vcc, exec, s[0:1]
	s_cbranch_vccz .LBB0_843
	s_mov_b64 s[40:41], s[76:77]
	s_mov_b64 s[38:39], s[76:77]
	s_mov_b64 s[0:1], s[76:77]
	s_lshl_b32 s16, s57, 20
	v_mov_b32_e32 v0, v252
	s_lshl_b64 s[4:5], s[16:17], 2
	s_add_u32 s0, s0, s4
	v_ashrrev_i32_e32 v4, 8, v0
	s_waitcnt vmcnt(0)
	v_and_b32_e32 v3, 0xff, v0
	v_readlane_b32 s4, v255, 4
	v_mov_b64_e32 v[0:1], s[2:3]
	s_addc_u32 s1, s1, s5
	v_lshl_add_u32 v2, v3, 2, s4
	v_mad_i64_i32 v[0:1], s[4:5], v4, s78, v[0:1]
	s_add_u32 s0, s0, 0x1a400000
	s_mov_b64 s[4:5], 0x300
	s_addc_u32 s1, s1, 0
	v_cmp_gt_i64_e32 vcc, s[4:5], v[0:1]
	v_mov_b32_e32 v102, 0
	v_mov_b32_e32 v103, 0
	v_mov_b32_e32 v104, 0
	v_mov_b32_e32 v105, 0
	s_and_saveexec_b64 s[42:43], vcc
	s_cbranch_execz .LBB0_743
	v_ashrrev_i32_e32 v1, 31, v0
	v_lshrrev_b32_e32 v1, 29, v1
	v_add_u32_e32 v1, v0, v1
	v_ashrrev_i32_e32 v5, 3, v1
	v_and_b32_e32 v1, -8, v1
	v_sub_u32_e32 v0, v0, v1
	v_cmp_gt_i32_e32 vcc, 0, v0
	s_mov_b32 s4, 0x2aaaaaab
	s_nop 0
	v_cndmask_b32_e32 v1, v246, v240, vcc
	v_mul_lo_u32 v0, v0, v1
	v_add_u32_e32 v0, v0, v5
	v_mul_hi_i32 v1, v0, s4
	v_lshrrev_b32_e32 v5, 31, v1
	v_ashrrev_i32_e32 v1, 3, v1
	v_add_u32_e32 v1, v1, v5
	v_lshlrev_b32_e32 v5, 3, v1
	v_sub_u32_e32 v6, 0x80, v5
	v_min_i32_e32 v6, 8, v6
	v_sub_u32_e32 v7, 0, v6
	v_max_i32_e32 v6, v6, v7
	v_cvt_f32_u32_e32 v7, v6
	v_mul_lo_u32 v1, v1, 48
	v_sub_u32_e32 v0, v0, v1
	v_sub_u32_e32 v8, 0, v0
	v_rcp_iflag_f32_e32 v7, v7
	v_ashrrev_i32_e32 v1, 31, v0
	v_max_i32_e32 v0, v0, v8
	v_sub_u32_e32 v8, 0, v6
	v_mul_f32_e32 v7, 0x4f7ffffe, v7
	v_cvt_u32_f32_e32 v7, v7
	v_mul_lo_u32 v8, v8, v7
	v_mul_hi_u32 v8, v7, v8
	v_add_u32_e32 v7, v7, v8
	v_mul_hi_u32 v7, v0, v7
	v_mul_lo_u32 v7, v7, v6
	v_sub_u32_e32 v0, v0, v7
	v_sub_u32_e32 v7, v0, v6
	v_cmp_ge_u32_e32 vcc, v0, v6
	s_nop 1
	v_cndmask_b32_e32 v0, v0, v7, vcc
	v_sub_u32_e32 v7, v0, v6
	v_cmp_ge_u32_e32 vcc, v0, v6
	s_nop 1
	v_cndmask_b32_e32 v0, v0, v7, vcc
	v_xor_b32_e32 v0, v0, v1
	v_sub_u32_e32 v0, v0, v1
	v_add_u32_e32 v0, v5, v0
	v_lshl_or_b32 v0, v0, 8, v3
	v_ashrrev_i32_e32 v1, 31, v0
	v_lshlrev_b64 v[0:1], 6, v[0:1]
	v_lshl_add_u64 v[0:1], s[0:1], 0, v[0:1]
	global_load_dwordx4 v[34:37], v[0:1], off
	global_load_dwordx4 v[38:41], v[0:1], off offset:32
	global_load_dwordx4 v[42:45], v[0:1], off offset:16
	global_load_dwordx4 v[46:49], v[0:1], off offset:48
	v_lshl_add_u32 v98, v4, 10, v2
	v_mov_b32_e32 v102, 1

.LBB0_1160:
	s_or_b64 exec, exec, s[0:1]
	s_mov_b64 s[40:41], s[76:77]
	s_mov_b64 s[0:1], s[76:77]
	s_mov_b64 s[4:5], s[76:77]
	s_waitcnt lgkmcnt(0)
	s_barrier
	s_lshl_b64 s[6:7], s[46:47], 2
	s_add_u32 s4, s4, s6
	v_mov_b32_e32 v0, v252
	s_addc_u32 s5, s5, s7
	s_add_u32 s42, s4, 0x1a400000
	v_ashrrev_i32_e32 v4, 8, v0
	v_and_b32_e32 v3, 0xff, v0
	v_readlane_b32 s4, v255, 4
	v_mov_b64_e32 v[0:1], s[2:3]
	s_addc_u32 s43, s5, 0
	v_lshl_add_u32 v2, v3, 2, s4
	v_mad_i64_i32 v[0:1], s[4:5], v4, s78, v[0:1]
	s_mov_b64 s[4:5], 0x800
	s_nop 0
	v_cmp_gt_i64_e32 vcc, s[4:5], v[0:1]
	v_mov_b32_e32 v102, 0
	v_mov_b32_e32 v103, 0
	v_mov_b32_e32 v104, 0
	v_mov_b32_e32 v105, 0
	s_and_saveexec_b64 s[46:47], vcc
	s_cbranch_execz .LBB0_1166
	v_ashrrev_i32_e32 v1, 31, v0
	v_lshrrev_b32_e32 v1, 29, v1
	v_add_u32_e32 v1, v0, v1
	v_and_b32_e32 v5, -8, v1
	v_sub_u32_e32 v5, v0, v5
	v_cmp_lt_i32_e32 vcc, -1, v5
	s_and_saveexec_b64 s[4:5], vcc
	s_xor_b64 s[48:49], exec, s[4:5]
	v_lshlrev_b32_e32 v0, 8, v5
	s_andn2_saveexec_b64 s[48:49], s[48:49]
	v_lshl_add_u32 v0, v5, 8, v5
	s_or_b64 exec, exec, s[48:49]
	v_ashrrev_i32_e32 v1, 3, v1
	v_add_u32_e32 v0, v0, v1
	v_ashrrev_i32_e32 v1, 31, v0
	v_lshrrev_b32_e32 v1, 25, v1
	v_add_u32_e32 v1, v0, v1
	v_ashrrev_i32_e32 v5, 7, v1
	v_lshlrev_b32_e32 v5, 3, v5
	v_sub_u32_e32 v6, 0x80, v5
	v_min_i32_e32 v6, 8, v6
	v_sub_u32_e32 v7, 0, v6
	v_max_i32_e32 v6, v6, v7
	v_cvt_f32_u32_e32 v7, v6
	v_and_b32_e32 v1, 0xffffff80, v1
	v_sub_u32_e32 v0, v0, v1
	v_sub_u32_e32 v8, 0, v0
	v_rcp_iflag_f32_e32 v7, v7
	v_ashrrev_i32_e32 v1, 31, v0
	v_max_i32_e32 v0, v0, v8
	v_sub_u32_e32 v8, 0, v6
	v_mul_f32_e32 v7, 0x4f7ffffe, v7
	v_cvt_u32_f32_e32 v7, v7
	v_mul_lo_u32 v8, v8, v7
	v_mul_hi_u32 v8, v7, v8
	v_add_u32_e32 v7, v7, v8
	v_mul_hi_u32 v7, v0, v7
	v_mul_lo_u32 v7, v7, v6
	v_sub_u32_e32 v0, v0, v7
	v_sub_u32_e32 v7, v0, v6
	v_cmp_ge_u32_e32 vcc, v0, v6
	s_nop 1
	v_cndmask_b32_e32 v0, v0, v7, vcc
	v_sub_u32_e32 v7, v0, v6
	v_cmp_ge_u32_e32 vcc, v0, v6
	s_nop 1
	v_cndmask_b32_e32 v0, v0, v7, vcc
	v_xor_b32_e32 v0, v0, v1
	v_sub_u32_e32 v0, v0, v1
	v_add_u32_e32 v0, v5, v0
	v_lshl_or_b32 v0, v0, 8, v3
	v_ashrrev_i32_e32 v1, 31, v0
	v_lshlrev_b64 v[0:1], 6, v[0:1]
	v_lshl_add_u64 v[0:1], s[42:43], 0, v[0:1]
	global_load_dwordx4 v[34:37], v[0:1], off
	global_load_dwordx4 v[38:41], v[0:1], off offset:32
	global_load_dwordx4 v[42:45], v[0:1], off offset:16
	global_load_dwordx4 v[46:49], v[0:1], off offset:48
	v_lshl_add_u32 v98, v4, 10, v2
	v_mov_b32_e32 v102, 1
.LBB0_1166:
	s_or_b64 exec, exec, s[46:47]
	v_add_u32_e32 v5, 2, v4
	v_mov_b64_e32 v[0:1], s[2:3]
	v_mad_i64_i32 v[0:1], s[4:5], v5, s78, v[0:1]
	s_mov_b64 s[4:5], 0x800
	s_nop 0
	v_cmp_gt_i64_e32 vcc, s[4:5], v[0:1]
	s_and_saveexec_b64 s[46:47], vcc
	s_cbranch_execz .LBB0_1172
	v_ashrrev_i32_e32 v1, 31, v0
	v_lshrrev_b32_e32 v1, 29, v1
	v_add_u32_e32 v1, v0, v1
	v_and_b32_e32 v6, -8, v1
	v_sub_u32_e32 v6, v0, v6
	v_cmp_lt_i32_e32 vcc, -1, v6
	s_and_saveexec_b64 s[4:5], vcc
	s_xor_b64 s[48:49], exec, s[4:5]
	v_lshlrev_b32_e32 v0, 8, v6
	s_andn2_saveexec_b64 s[48:49], s[48:49]
	v_lshl_add_u32 v0, v6, 8, v6
	s_or_b64 exec, exec, s[48:49]
	v_ashrrev_i32_e32 v1, 3, v1
	v_add_u32_e32 v0, v0, v1
	v_ashrrev_i32_e32 v1, 31, v0
	v_lshrrev_b32_e32 v1, 25, v1
	v_add_u32_e32 v1, v0, v1
	v_ashrrev_i32_e32 v6, 7, v1
	v_lshlrev_b32_e32 v6, 3, v6
	v_sub_u32_e32 v7, 0x80, v6
	v_min_i32_e32 v7, 8, v7
	v_sub_u32_e32 v8, 0, v7
	v_max_i32_e32 v7, v7, v8
	v_cvt_f32_u32_e32 v8, v7
	v_and_b32_e32 v1, 0xffffff80, v1
	v_sub_u32_e32 v0, v0, v1
	v_sub_u32_e32 v9, 0, v0
	v_rcp_iflag_f32_e32 v8, v8
	v_ashrrev_i32_e32 v1, 31, v0
	v_max_i32_e32 v0, v0, v9
	v_sub_u32_e32 v9, 0, v7
	v_mul_f32_e32 v8, 0x4f7ffffe, v8
	v_cvt_u32_f32_e32 v8, v8
	v_mul_lo_u32 v9, v9, v8
	v_mul_hi_u32 v9, v8, v9
	v_add_u32_e32 v8, v8, v9
	v_mul_hi_u32 v8, v0, v8
	v_mul_lo_u32 v8, v8, v7
	v_sub_u32_e32 v0, v0, v8
	v_sub_u32_e32 v8, v0, v7
	v_cmp_ge_u32_e32 vcc, v0, v7
	s_nop 1
	v_cndmask_b32_e32 v0, v0, v8, vcc
	v_sub_u32_e32 v8, v0, v7
	v_cmp_ge_u32_e32 vcc, v0, v7
	s_nop 1
	v_cndmask_b32_e32 v0, v0, v8, vcc
	v_xor_b32_e32 v0, v0, v1
	v_sub_u32_e32 v0, v0, v1
	v_add_u32_e32 v0, v6, v0
	v_lshl_or_b32 v0, v0, 8, v3
	v_ashrrev_i32_e32 v1, 31, v0
	v_lshlrev_b64 v[0:1], 6, v[0:1]
	v_lshl_add_u64 v[0:1], s[42:43], 0, v[0:1]
	global_load_dwordx4 v[50:53], v[0:1], off
	global_load_dwordx4 v[54:57], v[0:1], off offset:32
	global_load_dwordx4 v[58:61], v[0:1], off offset:16
	global_load_dwordx4 v[62:65], v[0:1], off offset:48
	v_lshl_add_u32 v99, v5, 10, v2
	v_mov_b32_e32 v103, 1
.LBB0_1172:
	s_or_b64 exec, exec, s[46:47]
	v_add_u32_e32 v5, 4, v4
	v_mov_b64_e32 v[0:1], s[2:3]
	v_mad_i64_i32 v[0:1], s[4:5], v5, s78, v[0:1]
	s_mov_b64 s[4:5], 0x800
	s_nop 0
	v_cmp_gt_i64_e32 vcc, s[4:5], v[0:1]
	s_and_saveexec_b64 s[46:47], vcc
	s_cbranch_execz .LBB0_1178
	v_ashrrev_i32_e32 v1, 31, v0
	v_lshrrev_b32_e32 v1, 29, v1
	v_add_u32_e32 v1, v0, v1
	v_and_b32_e32 v6, -8, v1
	v_sub_u32_e32 v6, v0, v6
	v_cmp_lt_i32_e32 vcc, -1, v6
	s_and_saveexec_b64 s[4:5], vcc
	s_xor_b64 s[48:49], exec, s[4:5]
	v_lshlrev_b32_e32 v0, 8, v6
	s_andn2_saveexec_b64 s[48:49], s[48:49]
	v_lshl_add_u32 v0, v6, 8, v6
	s_or_b64 exec, exec, s[48:49]
	v_ashrrev_i32_e32 v1, 3, v1
	v_add_u32_e32 v0, v0, v1
	v_ashrrev_i32_e32 v1, 31, v0
	v_lshrrev_b32_e32 v1, 25, v1
	v_add_u32_e32 v1, v0, v1
	v_ashrrev_i32_e32 v6, 7, v1
	v_lshlrev_b32_e32 v6, 3, v6
	v_sub_u32_e32 v7, 0x80, v6
	v_min_i32_e32 v7, 8, v7
	v_sub_u32_e32 v8, 0, v7
	v_max_i32_e32 v7, v7, v8
	v_cvt_f32_u32_e32 v8, v7
	v_and_b32_e32 v1, 0xffffff80, v1
	v_sub_u32_e32 v0, v0, v1
	v_sub_u32_e32 v9, 0, v0
	v_rcp_iflag_f32_e32 v8, v8
	v_ashrrev_i32_e32 v1, 31, v0
	v_max_i32_e32 v0, v0, v9
	v_sub_u32_e32 v9, 0, v7
	v_mul_f32_e32 v8, 0x4f7ffffe, v8
	v_cvt_u32_f32_e32 v8, v8
	v_mul_lo_u32 v9, v9, v8
	v_mul_hi_u32 v9, v8, v9
	v_add_u32_e32 v8, v8, v9
	v_mul_hi_u32 v8, v0, v8
	v_mul_lo_u32 v8, v8, v7
	v_sub_u32_e32 v0, v0, v8
	v_sub_u32_e32 v8, v0, v7
	v_cmp_ge_u32_e32 vcc, v0, v7
	s_nop 1
	v_cndmask_b32_e32 v0, v0, v8, vcc
	v_sub_u32_e32 v8, v0, v7
	v_cmp_ge_u32_e32 vcc, v0, v7
	s_nop 1
	v_cndmask_b32_e32 v0, v0, v8, vcc
	v_xor_b32_e32 v0, v0, v1
	v_sub_u32_e32 v0, v0, v1
	v_add_u32_e32 v0, v6, v0
	v_lshl_or_b32 v0, v0, 8, v3
	v_ashrrev_i32_e32 v1, 31, v0
	v_lshlrev_b64 v[0:1], 6, v[0:1]
	v_lshl_add_u64 v[0:1], s[42:43], 0, v[0:1]
	global_load_dwordx4 v[66:69], v[0:1], off
	global_load_dwordx4 v[70:73], v[0:1], off offset:32
	global_load_dwordx4 v[74:77], v[0:1], off offset:16
	global_load_dwordx4 v[78:81], v[0:1], off offset:48
	v_lshl_add_u32 v100, v5, 10, v2
	v_mov_b32_e32 v104, 1
.LBB0_1178:
	s_or_b64 exec, exec, s[46:47]
	v_add_u32_e32 v4, 6, v4
	v_mov_b64_e32 v[0:1], s[2:3]
	v_mad_i64_i32 v[0:1], s[4:5], v4, s78, v[0:1]
	s_mov_b64 s[4:5], 0x800
	s_nop 0
	v_cmp_gt_i64_e32 vcc, s[4:5], v[0:1]
	s_and_saveexec_b64 s[46:47], vcc
	s_cbranch_execz .LBB0_1184
	v_ashrrev_i32_e32 v1, 31, v0
	v_lshrrev_b32_e32 v1, 29, v1
	v_add_u32_e32 v1, v0, v1
	v_and_b32_e32 v5, -8, v1
	v_sub_u32_e32 v5, v0, v5
	v_cmp_lt_i32_e32 vcc, -1, v5
	s_and_saveexec_b64 s[4:5], vcc
	s_xor_b64 s[48:49], exec, s[4:5]
	v_lshlrev_b32_e32 v0, 8, v5
	s_andn2_saveexec_b64 s[48:49], s[48:49]
	v_lshl_add_u32 v0, v5, 8, v5
	s_or_b64 exec, exec, s[48:49]
	v_ashrrev_i32_e32 v1, 3, v1
	v_add_u32_e32 v0, v0, v1
	v_ashrrev_i32_e32 v1, 31, v0
	v_lshrrev_b32_e32 v1, 25, v1
	v_add_u32_e32 v1, v0, v1
	v_ashrrev_i32_e32 v5, 7, v1
	v_lshlrev_b32_e32 v5, 3, v5
	v_sub_u32_e32 v6, 0x80, v5
	v_min_i32_e32 v6, 8, v6
	v_sub_u32_e32 v7, 0, v6
	v_max_i32_e32 v6, v6, v7
	v_cvt_f32_u32_e32 v7, v6
	v_and_b32_e32 v1, 0xffffff80, v1
	v_sub_u32_e32 v0, v0, v1
	v_sub_u32_e32 v8, 0, v0
	v_rcp_iflag_f32_e32 v7, v7
	v_ashrrev_i32_e32 v1, 31, v0
	v_max_i32_e32 v0, v0, v8
	v_sub_u32_e32 v8, 0, v6
	v_mul_f32_e32 v7, 0x4f7ffffe, v7
	v_cvt_u32_f32_e32 v7, v7
	v_mul_lo_u32 v8, v8, v7
	v_mul_hi_u32 v8, v7, v8
	v_add_u32_e32 v7, v7, v8
	v_mul_hi_u32 v7, v0, v7
	v_mul_lo_u32 v7, v7, v6
	v_sub_u32_e32 v0, v0, v7
	v_sub_u32_e32 v7, v0, v6
	v_cmp_ge_u32_e32 vcc, v0, v6
	s_nop 1
	v_cndmask_b32_e32 v0, v0, v7, vcc
	v_sub_u32_e32 v7, v0, v6
	v_cmp_ge_u32_e32 vcc, v0, v6
	s_nop 1
	v_cndmask_b32_e32 v0, v0, v7, vcc
	v_xor_b32_e32 v0, v0, v1
	v_sub_u32_e32 v0, v0, v1
	v_add_u32_e32 v0, v5, v0
	v_lshl_or_b32 v0, v0, 8, v3
	v_ashrrev_i32_e32 v1, 31, v0
	v_lshlrev_b64 v[0:1], 6, v[0:1]
	v_lshl_add_u64 v[0:1], s[42:43], 0, v[0:1]
	global_load_dwordx4 v[82:85], v[0:1], off
	global_load_dwordx4 v[86:89], v[0:1], off offset:32
	global_load_dwordx4 v[90:93], v[0:1], off offset:16
	global_load_dwordx4 v[94:97], v[0:1], off offset:48
	v_lshl_add_u32 v101, v4, 10, v2
	v_mov_b32_e32 v105, 1
.LBB0_1184:
	s_or_b64 exec, exec, s[46:47]
	s_waitcnt vmcnt(0)
	v_cmp_ne_u32_e32 vcc, 0, v102
	s_and_saveexec_b64 s[46:47], vcc
	s_cbranch_execz .Lfr_3_0
	v_mov_b32_e32 v0, v34
	v_mov_b32_e32 v1, v38
	v_mov_b32_e32 v38, v35
	v_mov_b32_e32 v34, v36
	v_mov_b32_e32 v35, v40
	v_mov_b32_e32 v40, v37
	v_mov_b32_e32 v36, v42
	v_mov_b32_e32 v37, v46
	v_mov_b32_e32 v46, v43
	v_mov_b32_e32 v42, v44
	v_mov_b32_e32 v43, v48
	v_mov_b32_e32 v48, v45
	v_pk_add_f32 v[0:1], v[0:1], v[38:39]
	v_pk_add_f32 v[34:35], v[34:35], v[40:41]
	v_pk_add_f32 v[36:37], v[36:37], v[46:47]
	v_pk_add_f32 v[38:39], v[42:43], v[48:49]
	v_pk_add_f32 v[0:1], v[0:1], v[34:35]
	v_pk_add_f32 v[34:35], v[36:37], v[38:39]
	s_nop 0
	v_pk_add_f32 v[0:1], v[0:1], v[34:35]
	s_nop 0
	v_add_f32_e32 v0, v0, v1
	v_fmamk_f32 v0, v0, 0x3a800000, v236
	v_rsq_f32_e32 v0, v0
	ds_write_b32 v98, v0
.Lfr_3_0:
	s_or_b64 exec, exec, s[46:47]
	v_cmp_ne_u32_e32 vcc, 0, v103
	s_and_saveexec_b64 s[46:47], vcc
	s_cbranch_execz .Lfr_3_1
	v_mov_b32_e32 v0, v50
	v_mov_b32_e32 v1, v54
	v_mov_b32_e32 v54, v51
	v_mov_b32_e32 v50, v52
	v_mov_b32_e32 v51, v56
	v_mov_b32_e32 v56, v53
	v_mov_b32_e32 v52, v58
	v_mov_b32_e32 v53, v62
	v_mov_b32_e32 v62, v59
	v_mov_b32_e32 v58, v60
	v_mov_b32_e32 v59, v64
	v_mov_b32_e32 v64, v61
	v_pk_add_f32 v[0:1], v[0:1], v[54:55]
	v_pk_add_f32 v[50:51], v[50:51], v[56:57]
	v_pk_add_f32 v[52:53], v[52:53], v[62:63]
	v_pk_add_f32 v[54:55], v[58:59], v[64:65]
	v_pk_add_f32 v[0:1], v[0:1], v[50:51]
	v_pk_add_f32 v[50:51], v[52:53], v[54:55]
	s_nop 0
	v_pk_add_f32 v[0:1], v[0:1], v[50:51]
	s_nop 0
	v_add_f32_e32 v0, v0, v1
	v_fmamk_f32 v0, v0, 0x3a800000, v236
	v_rsq_f32_e32 v0, v0
	ds_write_b32 v99, v0
.Lfr_3_1:
	s_or_b64 exec, exec, s[46:47]
	v_cmp_ne_u32_e32 vcc, 0, v104
	s_and_saveexec_b64 s[46:47], vcc
	s_cbranch_execz .Lfr_3_2
	v_mov_b32_e32 v0, v66
	v_mov_b32_e32 v1, v70
	v_mov_b32_e32 v70, v67
	v_mov_b32_e32 v66, v68
	v_mov_b32_e32 v67, v72
	v_mov_b32_e32 v72, v69
	v_mov_b32_e32 v68, v74
	v_mov_b32_e32 v69, v78
	v_mov_b32_e32 v78, v75
	v_mov_b32_e32 v74, v76
	v_mov_b32_e32 v75, v80
	v_mov_b32_e32 v80, v77
	v_pk_add_f32 v[0:1], v[0:1], v[70:71]
	v_pk_add_f32 v[66:67], v[66:67], v[72:73]
	v_pk_add_f32 v[68:69], v[68:69], v[78:79]
	v_pk_add_f32 v[70:71], v[74:75], v[80:81]
	v_pk_add_f32 v[0:1], v[0:1], v[66:67]
	v_pk_add_f32 v[66:67], v[68:69], v[70:71]
	s_nop 0
	v_pk_add_f32 v[0:1], v[0:1], v[66:67]
	s_nop 0
	v_add_f32_e32 v0, v0, v1
	v_fmamk_f32 v0, v0, 0x3a800000, v236
	v_rsq_f32_e32 v0, v0
	ds_write_b32 v100, v0
.Lfr_3_2:
	s_or_b64 exec, exec, s[46:47]
	v_cmp_ne_u32_e32 vcc, 0, v105
	s_and_saveexec_b64 s[46:47], vcc
	s_cbranch_execz .Lfr_3_3
	v_mov_b32_e32 v0, v82
	v_mov_b32_e32 v1, v86
	v_mov_b32_e32 v86, v83
	v_mov_b32_e32 v82, v84
	v_mov_b32_e32 v83, v88
	v_mov_b32_e32 v88, v85
	v_mov_b32_e32 v84, v90
	v_mov_b32_e32 v85, v94
	v_mov_b32_e32 v94, v91
	v_mov_b32_e32 v90, v92
	v_mov_b32_e32 v91, v96
	v_mov_b32_e32 v96, v93
	v_pk_add_f32 v[0:1], v[0:1], v[86:87]
	v_pk_add_f32 v[82:83], v[82:83], v[88:89]
	v_pk_add_f32 v[84:85], v[84:85], v[94:95]
	v_pk_add_f32 v[86:87], v[90:91], v[96:97]
	v_pk_add_f32 v[0:1], v[0:1], v[82:83]
	v_pk_add_f32 v[82:83], v[84:85], v[86:87]
	s_nop 0
	v_pk_add_f32 v[0:1], v[0:1], v[82:83]
	s_nop 0
	v_add_f32_e32 v0, v0, v1
	v_fmamk_f32 v0, v0, 0x3a800000, v236
	v_rsq_f32_e32 v0, v0
	ds_write_b32 v101, v0
